# SSD phase: one static s_setprio 1 for waves 4-7 at phase entry (GEMM phases reset it)
# baseline (speedup 1.0000x reference)
; __device__ __forceinline__ void ssd_phase(const Ctx& C_, LAS unsigned char* lds_in, int l) {
;     ...
;     const int zt = tid >> 3, zv = tid & 7, bt = tid >> 4, bv = tid & 15;
;     const int pjs = wave & 3, ni0 = (wave >> 2) * 4;
;     const int NU = NBATCH * NH;
;     int u = C.bid; if (u >= NU) return;
;     bool sample; int b, h, r0, ntok; unsigned xoff, zoff, boff;
;     SSD_UNIT(u, sample, b, h, r0, ntok, xoff, zoff, boff);
;     u32x4 rx, zraw, rB[2], rC[2]; float dtraw = 0.f;
;     SSD_PREFETCH(r0, ntok, h, xoff, zoff, boff, 0);
.LBB0_630:
	s_or_b64 exec, exec, s[2:3]
	s_waitcnt lgkmcnt(0)
	v_mov_b32_e32 v1, v174
	s_mov_b32 s33, s75
	s_mov_b32 s63, s74
	s_mov_b32 s59, s70
	v_readlane_b32 s4, v255, 3
	s_lshl_b32 s76, s78, 5
	s_barrier
	s_mov_b32 s44, s77
	v_readlane_b32 s5, v255, 4
	s_cmpk_gt_i32 s59, 0xff
	s_cbranch_scc1 .LBB0_714
	s_load_dwordx4 s[48:51], s[4:5], 0xd0
	s_cmp_lt_u32 s33, 4
	s_cbranch_scc1 .Lssd_prio_skip
	s_setprio 1
.Lssd_prio_skip:
	v_lshl_add_u32 v96, s33, 6, v1
	v_ashrrev_i32_e32 v97, 3, v96
	s_waitcnt vmcnt(0)
	v_lshlrev_b32_e32 v10, 3, v96
	v_and_b32_e32 v28, 56, v10
	s_waitcnt lgkmcnt(0)
	s_add_u32 s72, s50, 0x10e94000
	s_addc_u32 s73, s51, 0
	s_ashr_i32 s0, s59, 31
	s_lshr_b32 s0, s0, 27
	s_add_i32 s0, s59, s0
	s_ashr_i32 s60, s0, 5
	s_andn2_b32 s0, s0, 31
	s_sub_i32 s74, s59, s0
	s_movk_i32 s0, 0x2100
	v_mul_lo_u32 v2, v97, s0
	s_lshl_b32 s8, s74, 6
	v_add_u32_e32 v30, 0x400, v2
	v_add_u32_e32 v2, s8, v30
	v_or_b32_e32 v72, v2, v28
	v_mov_b32_e32 v2, v0
	s_mul_i32 s61, s60, 0x810
	v_mov_b32_e32 v4, v2
	v_mov_b32_e32 v5, v2
	v_mov_b32_e32 v3, v2
	v_mov_b64_e32 v[8:9], v[4:5]
	v_cmp_gt_i32_e64 s[2:3], 64, v97
	v_mov_b64_e32 v[6:7], v[2:3]
	s_and_saveexec_b64 s[6:7], s[2:3]
	s_cbranch_execz .LBB0_633
	s_mul_i32 s0, s61, 0x4200
	s_mul_hi_i32 s1, s61, 0x4200
	s_add_u32 s0, s72, s0
	s_addc_u32 s1, s73, s1
	v_mov_b32_e32 v73, v0
	v_lshl_add_u64 v[6:7], v[72:73], 1, s[0:1]
	global_load_dwordx4 v[6:9], v[6:7], off
